# v94 + all nine grid barriers on one shorter hand-written protocol: static generations, last arriver of an XCC adds to the top counter without waiting for a return, everyone polls the top counter; no d
# baseline (speedup 1.0000x reference)
; __device__ __forceinline__ unsigned xb_ld(unsigned* p)              { return __hip_atomic_load(p, __ATOMIC_RELAXED, __HIP_MEMORY_SCOPE_AGENT); }
; __device__ __forceinline__ unsigned xb_add(unsigned* p, unsigned v) { return __hip_atomic_fetch_add(p, v, __ATOMIC_RELAXED, __HIP_MEMORY_SCOPE_AGENT); }
; #define XB_SPIN(cond, bar) do { unsigned _sp = 0; while (cond) { __builtin_amdgcn_s_sleep(1); \
;     if ((++_sp & 255u) == 0u) { if (xb_ld(&(bar)[XB_TMO])) break; if (_sp > XB_SPIN_CAP) { atomicAdd(&(bar)[XB_TMO], 1u); break; } } } } while (0)
; __device__ __forceinline__ void xcd_barrier(const XcdBarrier& b) {
;     asm volatile("s_waitcnt vmcnt(0)" ::: "memory");
;     __syncthreads();
;     if (threadIdx.x == 0) {
;         unsigned* bar = b.bar;
;         __builtin_amdgcn_s_waitcnt(0);
;         unsigned nloc = b.st[0], nx = b.st[1];
;         if (nloc == 0u) { xcd_barrier_complete(bar, b.x, nloc, nx); b.st[0] = nloc; b.st[1] = nx; }
;         const unsigned old = xb_add(&bar[XB_XSUB(b.x)], 1u);
;         const unsigned gen = old / nloc;
;         if (old + 1u == (gen + 1u) * nloc) {
;             __builtin_amdgcn_fence(__ATOMIC_RELEASE, "agent");
;             asm volatile("s_waitcnt vmcnt(0)" ::: "memory");
;             const unsigned og = xb_add(&bar[XB_TOP], 1u);
;             const unsigned tg = og / nx;
;             if (og + 1u == (tg + 1u) * nx) xb_add(&bar[XB_TOPGEN], 1u);
;             else XB_SPIN(xb_ld(&bar[XB_TOPGEN]) == tg, bar);
;             __builtin_amdgcn_fence(__ATOMIC_ACQUIRE, "agent");
;             xb_add(&bar[XB_XGEN(b.x)], 1u);
.Lgb0_census_ok:
	s_max_u32 s11, s11, 1
	s_max_u32 s22, s10, 1
	v_mov_b32_e32 v6, 0x23fc0
	v_mov_b32_e32 v7, s11
	ds_write_b32 v6, v7
	v_mov_b32_e32 v7, s22
	ds_write_b32 v6, v7 offset:4
	s_add_i32 s23, s8, 0x1000
	v_mov_b32_e32 v4, s23
	global_atomic_add v6, v4, v1, s[84:85] offset:1024 sc0
	s_waitcnt vmcnt(0) lgkmcnt(0)
	v_readfirstlane_b32 s9, v6
	s_add_i32 s9, s9, 1
	v_mov_b32_e32 v4, 0x3000
	s_mov_b32 s24, 0
	s_cmp_eq_u32 s9, s11
	s_cbranch_scc0 .Lgb0_poll
	buffer_wbl2 sc1
	s_waitcnt vmcnt(0)
	global_atomic_add v4, v1, s[84:85] offset:1024
.Lgb0_poll:
	global_load_dword v6, v4, s[84:85] offset:1024 sc1
	s_waitcnt vmcnt(0)
	v_readfirstlane_b32 s9, v6
	s_cmp_ge_u32 s9, s22
	s_cbranch_scc1 .Lgb0_fin
	s_sleep 1
	s_add_u32 s24, s24, 1
	s_cmp_lt_u32 s24, 0x18000
	s_cbranch_scc1 .Lgb0_poll

; __device__ __forceinline__ unsigned xb_ld(unsigned* p)              { return __hip_atomic_load(p, __ATOMIC_RELAXED, __HIP_MEMORY_SCOPE_AGENT); }
; __device__ __forceinline__ unsigned xb_add(unsigned* p, unsigned v) { return __hip_atomic_fetch_add(p, v, __ATOMIC_RELAXED, __HIP_MEMORY_SCOPE_AGENT); }
; #define XB_SPIN(cond, bar) do { unsigned _sp = 0; while (cond) { __builtin_amdgcn_s_sleep(1); \
;     if ((++_sp & 255u) == 0u) { if (xb_ld(&(bar)[XB_TMO])) break; if (_sp > XB_SPIN_CAP) { atomicAdd(&(bar)[XB_TMO], 1u); break; } } } } while (0)
; __device__ __forceinline__ void xcd_barrier(const XcdBarrier& b) {
;     asm volatile("s_waitcnt vmcnt(0)" ::: "memory");
;     __syncthreads();
;     if (threadIdx.x == 0) {
;         unsigned* bar = b.bar;
;         __builtin_amdgcn_s_waitcnt(0);
;         unsigned nloc = b.st[0], nx = b.st[1];
;         if (nloc == 0u) { xcd_barrier_complete(bar, b.x, nloc, nx); b.st[0] = nloc; b.st[1] = nx; }
;         const unsigned old = xb_add(&bar[XB_XSUB(b.x)], 1u);
;         const unsigned gen = old / nloc;
;         if (old + 1u == (gen + 1u) * nloc) {
;             __builtin_amdgcn_fence(__ATOMIC_RELEASE, "agent");
;             asm volatile("s_waitcnt vmcnt(0)" ::: "memory");
;             const unsigned og = xb_add(&bar[XB_TOP], 1u);
;             const unsigned tg = og / nx;
;             if (og + 1u == (tg + 1u) * nx) xb_add(&bar[XB_TOPGEN], 1u);
;             else XB_SPIN(xb_ld(&bar[XB_TOPGEN]) == tg, bar);
;             __builtin_amdgcn_fence(__ATOMIC_ACQUIRE, "agent");
;             xb_add(&bar[XB_XGEN(b.x)], 1u);
; __global__ void __launch_bounds__(512) fwd_kernel(Params p_unused) {
;     ...
;     xcd_barrier(xb);
.LBB0_178:
	s_waitcnt vmcnt(0)
	s_waitcnt vmcnt(0)
	s_barrier
	s_mov_b64 s[0:1], exec
	v_readlane_b32 s4, v252, 6
	v_readlane_b32 s5, v252, 7
	s_and_b64 s[4:5], s[0:1], s[4:5]
	s_mov_b64 exec, s[4:5]
	s_cbranch_execz .LBB0_236
	s_waitcnt vmcnt(0) expcnt(0) lgkmcnt(0)
	buffer_inv sc1
	v_mov_b32_e32 v0, 0x23fc0
	ds_read_b32 v2, v0
	ds_read_b32 v3, v0 offset:4
	v_readlane_b32 s3, v252, 5
	s_lshl_b32 s8, s3, 8
	v_mov_b32_e32 v1, 1
	s_add_i32 s23, s8, 0x1000
	v_mov_b32_e32 v4, s23
	global_atomic_add v6, v4, v1, s[84:85] offset:1024 sc0
	s_waitcnt vmcnt(0) lgkmcnt(0)
	v_readfirstlane_b32 s9, v6
	v_readfirstlane_b32 s11, v2
	v_readfirstlane_b32 s22, v3
	s_mul_i32 s11, s11, 2
	s_mul_i32 s22, s22, 2
	s_add_i32 s9, s9, 1
	v_mov_b32_e32 v4, 0x3000
	s_mov_b32 s24, 0
	s_cmp_eq_u32 s9, s11
	s_cbranch_scc0 .Lgb1_poll
	buffer_wbl2 sc1
	s_waitcnt vmcnt(0)
	global_atomic_add v4, v1, s[84:85] offset:1024

; __device__ __forceinline__ void xcd_barrier(const XcdBarrier& b) {
;     asm volatile("s_waitcnt vmcnt(0)" ::: "memory");
;     __syncthreads();
;     if (threadIdx.x == 0) {
;         unsigned* bar = b.bar;
;         __builtin_amdgcn_s_waitcnt(0);
;         unsigned nloc = b.st[0], nx = b.st[1];
;         if (nloc == 0u) { xcd_barrier_complete(bar, b.x, nloc, nx); b.st[0] = nloc; b.st[1] = nx; }
.Lgb1_fin:
	s_waitcnt vmcnt(0) lgkmcnt(0)
	s_branch .LBB0_236
	s_add_i32 s3, 0, 0x23fc0
	v_mov_b32_e32 v0, s3
	s_waitcnt vmcnt(0) expcnt(0) lgkmcnt(0)
	ds_read_b32 v2, v0
	s_add_i32 s3, 0, 0x23fc4
	v_mov_b32_e32 v0, s3
	ds_read_b32 v0, v0
	s_waitcnt lgkmcnt(1)
	v_cmp_ne_u32_e32 vcc, 0, v2
	s_cbranch_vccnz .LBB0_200
	s_add_u32 s4, s82, 0x38a00200
	s_addc_u32 s5, s83, 0
	s_add_u32 s6, s82, 0x38a00400
	s_addc_u32 s7, s83, 0
	s_add_u32 s8, s82, 0x38a00500
	s_addc_u32 s9, s83, 0
	s_add_u32 s10, s82, 0x38a00600
	s_addc_u32 s11, s83, 0
	s_add_u32 s14, s82, 0x38a00700
	s_addc_u32 s15, s83, 0
	s_add_u32 s16, s82, 0x38a00800
	s_addc_u32 s17, s83, 0
	s_add_u32 s18, s82, 0x38a00900
	s_addc_u32 s19, s83, 0
	s_add_u32 s20, s82, 0x38a00a00
	s_addc_u32 s21, s83, 0
	s_add_u32 s22, s82, 0x38a00b00
	s_addc_u32 s23, s83, 0
	s_add_u32 s24, s82, 0x38a00c00
	s_addc_u32 s25, s83, 0
	s_add_u32 s26, s82, 0x38a00d00
	s_addc_u32 s27, s83, 0
	s_add_u32 s28, s82, 0x38a00e00
	s_addc_u32 s29, s83, 0
	s_add_u32 s30, s82, 0x38a00f00
	s_addc_u32 s31, s83, 0
	s_add_u32 s34, s82, 0x38a01000
	s_addc_u32 s35, s83, 0
	s_add_u32 s36, s82, 0x38a01100
	s_addc_u32 s37, s83, 0
	s_add_u32 s38, s82, 0x38a01200
	v_readlane_b32 s3, v252, 0
	s_addc_u32 s39, s83, 0
	s_mul_i32 s3, s93, s3
	s_add_u32 s42, s82, 0x38a01300
	s_mul_i32 s3, s3, s92
	s_addc_u32 s43, s83, 0
	s_mov_b32 s33, 1
	v_mov_b32_e32 v16, 0
	s_branch .LBB0_182

; __device__ __forceinline__ void vt_unit(const Params& p, int unit, bfu* tile  ) {
;     const int blk = unit & 15, bh = unit >> 4, h = bh & 15, b = bh >> 4, t0 = blk * 256, tid = threadIdx.x;
;     const bfu* proj = (const bfu*)(p.ws + WS_PROJ);
;     bfu* vt = (bfu*)(p.ws + WS_VT);
; #pragma unroll
;     for (int i = 0; i < 4; ++i) {
;         const int e = tid + 512 * i, t = e >> 3, d8 = (e & 7) * 8;
;         const uint4 v = *(const uint4*)(proj + (size_t)(b * 4096 + t0 + t) * NPROJ + 2048 + h * 64 + d8);
; __device__ __forceinline__ void phase2(const Params& p, unsigned char* lds, int bid, int G) {
;     constexpr int U_CP = 0, U_CS = 32, U_VT = 1024, U_DT = 130, NU = U_CP + U_CS + U_VT + U_DT;
;     const int tid = threadIdx.x;
;     for (int u = bid; u < NU; u += G) {
;         int j = u;
;         if (j < U_VT) { vt_unit(p, j, (bfu*)lds); continue; }
.LBB0_235:
	s_or_b64 exec, exec, s[8:9]
	s_waitcnt vmcnt(0)
.LBB0_236:
	s_or_b64 exec, exec, s[0:1]
	v_readlane_b32 s0, v252, 1
	v_bfe_u32 v175, v172, 4, 2
	v_readlane_b32 s1, v252, 2
	s_cmpk_gt_i32 s2, 0x4a1
	v_lshrrev_b32_e32 v194, 6, v172
	v_and_b32_e32 v174, 15, v172
	v_lshlrev_b32_e32 v181, 3, v172
	v_lshrrev_b32_e32 v76, 3, v172
	v_lshlrev_b32_e32 v176, 4, v175
	s_waitcnt lgkmcnt(0)
	s_barrier
	s_cbranch_scc1 .LBB0_279
	s_movk_i32 s3, 0xff
	v_cmp_lt_u32_e64 s[10:11], s3, v172
	v_and_b32_e32 v0, 56, v181
	s_movk_i32 s3, 0x214
	v_add_u32_e32 v3, 0x200, v172
	v_or_b32_e32 v4, 0x400, v172
	v_add_u32_e32 v5, 0x600, v172
	v_mad_u32_u24 v1, v0, s3, 0
	v_lshrrev_b32_e32 v100, 3, v3
	v_lshrrev_b32_e32 v102, 3, v4
	v_lshrrev_b32_e32 v104, 3, v5
	v_lshl_add_u32 v99, v76, 1, v1
	v_lshl_add_u32 v101, v100, 1, v1
	v_lshl_add_u32 v103, v102, 1, v1
	v_lshl_add_u32 v105, v104, 1, v1
	v_and_b32_e32 v1, 31, v172
	v_lshlrev_b32_e32 v2, 3, v1
	v_lshl_add_u32 v108, v1, 4, 0
	v_bfe_u32 v1, v172, 3, 2
	v_lshrrev_b32_e32 v109, 5, v3
	v_lshrrev_b32_e32 v111, 5, v4
	v_lshlrev_b32_e32 v3, 1, v1
	v_lshlrev_b32_e32 v4, 3, v0
	v_and_b32_e32 v6, 8, v181
	v_add3_u32 v115, 0, v3, v4
	v_lshlrev_b32_e32 v4, 10, v1
	v_and_b32_e32 v1, 30, v172
	v_lshlrev_b32_e32 v3, 5, v6
	v_add3_u32 v116, 0, v1, v3
	v_lshlrev_b32_e32 v1, 7, v172
	v_and_b32_e32 v8, 0xf00, v1
	v_lshlrev_b32_e32 v1, 14, v194
	v_lshl_add_u32 v1, s2, 17, v1
	v_mov_b32_e32 v65, 0
	v_and_b32_e32 v77, 12, v194
	v_lshrrev_b32_e32 v106, 5, v172
	v_lshrrev_b32_e32 v113, 5, v5
	v_lshlrev_b32_e32 v68, 4, v175
	v_lshl_or_b32 v1, v174, 10, v1
	v_or_b32_e32 v67, 0xffffdf00, v194
	v_and_b32_e32 v66, 0x7f8, v181
	s_mov_b32 s5, 0
	v_cmp_ne_u32_e64 s[6:7], 0, v77
	v_cmp_lt_u32_e64 s[8:9], 4, v77
	v_add_u32_e32 v92, -5, v77
	v_or_b32_e32 v93, 1, v77
	v_add_u32_e32 v94, -4, v77
	v_or_b32_e32 v95, 2, v77
	v_add_u32_e32 v96, -3, v77
	v_or_b32_e32 v97, 3, v194
	v_add_u32_e32 v98, -2, v77
	v_mul_u32_u24_e32 v107, 0x214, v106
	v_mul_u32_u24_e32 v110, 0x214, v109
	v_mul_u32_u24_e32 v112, 0x214, v111
	v_mul_u32_u24_e32 v114, 0x214, v113
	v_lshl_or_b32 v117, v175, 6, v174
	v_mov_b32_e32 v69, v65
	v_add_u32_e32 v70, 0xf7c00000, v1
	s_lshl_b32 s3, s92, 17
	v_lshl_or_b32 v72, v174, 11, v68
	v_mov_b32_e32 v73, v65
	s_movk_i32 s33, 0x410
	v_lshlrev_b32_e32 v118, 2, v174
	s_mov_b32 s41, 0x41a00000
	s_mov_b32 s44, 0x3f2aaaab
	v_mov_b32_e32 v119, 0x3ecc95a3
	s_mov_b32 s45, 0x3f317218
	s_mov_b32 s46, 0x7f800000
	s_mov_b32 s47, 0x33800000
	s_mov_b64 s[14:15], 0x16600000
	s_mov_b64 s[16:17], 0x2000
	s_mov_b64 s[18:19], 0x4000
	s_mov_b64 s[20:21], 0x6000
	s_movk_i32 s48, 0x2000
	s_movk_i32 s49, 0x3000
	s_mov_b64 s[22:23], 0x16800000
	s_mov_b64 s[24:25], 0x9518000
	v_lshlrev_b32_e32 v74, 1, v0
	s_mov_b32 s50, 0x4301000
	v_lshlrev_b32_e32 v78, 1, v2
	s_mov_b64 s[26:27], 0x10600000
	v_lshlrev_b32_e32 v80, 1, v4
	s_mov_b64 s[28:29], 0x12600000
	v_lshlrev_b32_e32 v82, 1, v8
	v_lshlrev_b32_e32 v84, 1, v6
	s_mov_b64 s[30:31], 0x14600000
	v_mov_b32_e32 v86, 0x3f317218
	v_mov_b32_e32 v120, 0x7f800000
	v_mov_b32_e32 v121, 0x7fc00000
	v_mov_b32_e32 v122, 0xff800000
	s_mov_b32 s51, s2
	s_mov_b32 s54, s2
	s_lshl_b32 s55, s54, 8
	s_and_b32 s55, s55, 0xf00
	s_lshl_b32 s56, s54, 4
	s_and_b32 s56, s56, 0xfffff000
	s_or_b32 s55, s56, s55
	s_lshl_b32 s56, s54, 3
	s_and_b32 s56, s56, 0x780
	s_load_dwordx2 s[58:59], s[0:1], 0xb8
	s_waitcnt lgkmcnt(0)
	s_add_u32 s58, s58, s56
	s_addc_u32 s59, s59, 0
	s_add_u32 s58, s58, s50
	s_addc_u32 s59, s59, 0
	v_mov_b32_e32 v158, s58
	v_mov_b32_e32 v159, s59
	v_mov_b32_e32 v160, v74
	v_mov_b32_e32 v161, 0
	v_lshl_add_u64 v[158:159], v[158:159], 0, v[160:161]
	v_or_b32_e32 v160, s55, v76
	v_mad_i64_i32 v[162:163], s[60:61], v160, s49, v[158:159]
	global_load_dwordx4 v[142:145], v[162:163], off
	v_or_b32_e32 v160, s55, v100
	v_mad_i64_i32 v[162:163], s[60:61], v160, s49, v[158:159]
	global_load_dwordx4 v[146:149], v[162:163], off
	v_or_b32_e32 v160, s55, v102
	v_mad_i64_i32 v[162:163], s[60:61], v160, s49, v[158:159]
	global_load_dwordx4 v[150:153], v[162:163], off
	v_add_u32_e32 v160, s55, v104
	v_mad_i64_i32 v[162:163], s[60:61], v160, s49, v[158:159]
	global_load_dwordx4 v[154:157], v[162:163], off
	s_branch .LBB0_239

; __device__ __forceinline__ unsigned xb_ld(unsigned* p)              { return __hip_atomic_load(p, __ATOMIC_RELAXED, __HIP_MEMORY_SCOPE_AGENT); }
; __device__ __forceinline__ unsigned xb_add(unsigned* p, unsigned v) { return __hip_atomic_fetch_add(p, v, __ATOMIC_RELAXED, __HIP_MEMORY_SCOPE_AGENT); }
; #define XB_SPIN(cond, bar) do { unsigned _sp = 0; while (cond) { __builtin_amdgcn_s_sleep(1); \
;     if ((++_sp & 255u) == 0u) { if (xb_ld(&(bar)[XB_TMO])) break; if (_sp > XB_SPIN_CAP) { atomicAdd(&(bar)[XB_TMO], 1u); break; } } } } while (0)
; __device__ __forceinline__ void xcd_barrier(const XcdBarrier& b) {
;     asm volatile("s_waitcnt vmcnt(0)" ::: "memory");
;     __syncthreads();
;     if (threadIdx.x == 0) {
;         unsigned* bar = b.bar;
;         __builtin_amdgcn_s_waitcnt(0);
;         unsigned nloc = b.st[0], nx = b.st[1];
;         if (nloc == 0u) { xcd_barrier_complete(bar, b.x, nloc, nx); b.st[0] = nloc; b.st[1] = nx; }
;         const unsigned old = xb_add(&bar[XB_XSUB(b.x)], 1u);
;         const unsigned gen = old / nloc;
;         if (old + 1u == (gen + 1u) * nloc) {
;             __builtin_amdgcn_fence(__ATOMIC_RELEASE, "agent");
;             asm volatile("s_waitcnt vmcnt(0)" ::: "memory");
;             const unsigned og = xb_add(&bar[XB_TOP], 1u);
;             const unsigned tg = og / nx;
;             if (og + 1u == (tg + 1u) * nx) xb_add(&bar[XB_TOPGEN], 1u);
;             else XB_SPIN(xb_ld(&bar[XB_TOPGEN]) == tg, bar);
;             __builtin_amdgcn_fence(__ATOMIC_ACQUIRE, "agent");
;             xb_add(&bar[XB_XGEN(b.x)], 1u);
; __global__ void __launch_bounds__(512) fwd_kernel(Params p_unused) {
;     ...
;     xcd_barrier(xb);
.LBB0_279:
	s_waitcnt vmcnt(0)
	s_barrier
	s_mov_b64 s[0:1], exec
	v_readlane_b32 s4, v252, 6
	v_readlane_b32 s5, v252, 7
	s_and_b64 s[4:5], s[0:1], s[4:5]
	s_mov_b64 exec, s[4:5]
	s_cbranch_execz .LBB0_331
	s_waitcnt vmcnt(0) expcnt(0) lgkmcnt(0)
	buffer_inv sc1
	v_mov_b32_e32 v0, 0x23fc0
	ds_read_b32 v2, v0
	ds_read_b32 v3, v0 offset:4
	v_readlane_b32 s3, v252, 5
	s_lshl_b32 s8, s3, 8
	v_mov_b32_e32 v1, 1
	s_add_i32 s23, s8, 0x1000
	v_mov_b32_e32 v4, s23
	global_atomic_add v6, v4, v1, s[84:85] offset:1024 sc0
	s_waitcnt vmcnt(0) lgkmcnt(0)
	v_readfirstlane_b32 s9, v6
	v_readfirstlane_b32 s11, v2
	v_readfirstlane_b32 s22, v3
	s_mul_i32 s11, s11, 3
	s_mul_i32 s22, s22, 3
	s_add_i32 s9, s9, 1
	v_mov_b32_e32 v4, 0x3000
	s_mov_b32 s24, 0
	s_cmp_eq_u32 s9, s11
	s_cbranch_scc0 .Lgb2_poll
	buffer_wbl2 sc1
	s_waitcnt vmcnt(0)
	global_atomic_add v4, v1, s[84:85] offset:1024

; __device__ __forceinline__ unsigned xb_ld(unsigned* p)              { return __hip_atomic_load(p, __ATOMIC_RELAXED, __HIP_MEMORY_SCOPE_AGENT); }
; __device__ __forceinline__ unsigned xb_add(unsigned* p, unsigned v) { return __hip_atomic_fetch_add(p, v, __ATOMIC_RELAXED, __HIP_MEMORY_SCOPE_AGENT); }
; #define XB_SPIN(cond, bar) do { unsigned _sp = 0; while (cond) { __builtin_amdgcn_s_sleep(1); \
;     if ((++_sp & 255u) == 0u) { if (xb_ld(&(bar)[XB_TMO])) break; if (_sp > XB_SPIN_CAP) { atomicAdd(&(bar)[XB_TMO], 1u); break; } } } } while (0)
; __device__ __forceinline__ void xcd_barrier(const XcdBarrier& b) {
;     asm volatile("s_waitcnt vmcnt(0)" ::: "memory");
;     __syncthreads();
;     if (threadIdx.x == 0) {
;         unsigned* bar = b.bar;
;         __builtin_amdgcn_s_waitcnt(0);
;         unsigned nloc = b.st[0], nx = b.st[1];
;         if (nloc == 0u) { xcd_barrier_complete(bar, b.x, nloc, nx); b.st[0] = nloc; b.st[1] = nx; }
;         const unsigned old = xb_add(&bar[XB_XSUB(b.x)], 1u);
;         const unsigned gen = old / nloc;
;         if (old + 1u == (gen + 1u) * nloc) {
;             __builtin_amdgcn_fence(__ATOMIC_RELEASE, "agent");
;             asm volatile("s_waitcnt vmcnt(0)" ::: "memory");
;             const unsigned og = xb_add(&bar[XB_TOP], 1u);
;             const unsigned tg = og / nx;
;             if (og + 1u == (tg + 1u) * nx) xb_add(&bar[XB_TOPGEN], 1u);
;             else XB_SPIN(xb_ld(&bar[XB_TOPGEN]) == tg, bar);
;             __builtin_amdgcn_fence(__ATOMIC_ACQUIRE, "agent");
;             xb_add(&bar[XB_XGEN(b.x)], 1u);
; __global__ void __launch_bounds__(512) fwd_kernel(Params p_unused) {
;     ...
;     xcd_barrier(xb);
.LBB0_413:
	s_waitcnt vmcnt(0)
	s_barrier
	s_mov_b64 s[0:1], exec
	v_readlane_b32 s4, v252, 6
	v_readlane_b32 s5, v252, 7
	s_and_b64 s[4:5], s[0:1], s[4:5]
	s_mov_b64 exec, s[4:5]
	s_cbranch_execz .LBB0_465
	s_waitcnt vmcnt(0) expcnt(0) lgkmcnt(0)
	buffer_inv sc1
	v_mov_b32_e32 v0, 0x23fc0
	ds_read_b32 v2, v0
	ds_read_b32 v3, v0 offset:4
	v_readlane_b32 s3, v252, 5
	s_lshl_b32 s8, s3, 8
	v_mov_b32_e32 v1, 1
	s_add_i32 s23, s8, 0x1000
	v_mov_b32_e32 v4, s23
	global_atomic_add v6, v4, v1, s[84:85] offset:1024 sc0
	s_waitcnt vmcnt(0) lgkmcnt(0)
	v_readfirstlane_b32 s9, v6
	v_readfirstlane_b32 s11, v2
	v_readfirstlane_b32 s22, v3
	s_mul_i32 s11, s11, 4
	s_mul_i32 s22, s22, 4
	s_add_i32 s9, s9, 1
	v_mov_b32_e32 v4, 0x3000
	s_mov_b32 s24, 0
	s_cmp_eq_u32 s9, s11
	s_cbranch_scc0 .Lgb3_poll
	buffer_wbl2 sc1
	s_waitcnt vmcnt(0)
	global_atomic_add v4, v1, s[84:85] offset:1024

; __device__ __forceinline__ void xcd_barrier(const XcdBarrier& b) {
;     asm volatile("s_waitcnt vmcnt(0)" ::: "memory");
;     __syncthreads();
;     if (threadIdx.x == 0) {
;         unsigned* bar = b.bar;
;         __builtin_amdgcn_s_waitcnt(0);
;         unsigned nloc = b.st[0], nx = b.st[1];
;         if (nloc == 0u) { xcd_barrier_complete(bar, b.x, nloc, nx); b.st[0] = nloc; b.st[1] = nx; }
.Lgb3_fin:
	s_waitcnt vmcnt(0) lgkmcnt(0)
	s_branch .LBB0_465
	s_add_i32 s3, 0, 0x23fc0
	v_mov_b32_e32 v0, s3
	s_waitcnt vmcnt(0) expcnt(0) lgkmcnt(0)
	ds_read_b32 v2, v0
	s_add_i32 s3, 0, 0x23fc4
	v_mov_b32_e32 v0, s3
	ds_read_b32 v0, v0
	s_waitcnt lgkmcnt(1)
	v_cmp_ne_u32_e32 vcc, 0, v2
	s_cbranch_vccnz .LBB0_429
	s_add_u32 s4, s82, 0x38a00200
	s_addc_u32 s5, s83, 0
	s_add_u32 s8, s82, 0x38a00400
	s_addc_u32 s9, s83, 0
	s_add_u32 s10, s82, 0x38a00500
	s_addc_u32 s11, s83, 0
	s_add_u32 s12, s82, 0x38a00600
	s_addc_u32 s13, s83, 0
	s_add_u32 s14, s82, 0x38a00700
	s_addc_u32 s15, s83, 0
	s_add_u32 s16, s82, 0x38a00800
	s_addc_u32 s17, s83, 0
	s_add_u32 s18, s82, 0x38a00900
	s_addc_u32 s19, s83, 0
	s_add_u32 s20, s82, 0x38a00a00
	s_addc_u32 s21, s83, 0
	s_add_u32 s22, s82, 0x38a00b00
	s_addc_u32 s23, s83, 0
	s_add_u32 s24, s82, 0x38a00c00
	s_addc_u32 s25, s83, 0
	s_add_u32 s26, s82, 0x38a00d00
	s_addc_u32 s27, s83, 0
	s_add_u32 s28, s82, 0x38a00e00
	s_addc_u32 s29, s83, 0
	s_add_u32 s30, s82, 0x38a00f00
	s_addc_u32 s31, s83, 0
	s_add_u32 s34, s82, 0x38a01000
	s_addc_u32 s35, s83, 0
	s_add_u32 s36, s82, 0x38a01100
	s_addc_u32 s37, s83, 0
	s_add_u32 s38, s82, 0x38a01200
	v_readlane_b32 s3, v252, 0
	s_addc_u32 s39, s83, 0
	s_mul_i32 s3, s93, s3
	s_add_u32 s42, s82, 0x38a01300
	s_mul_i32 s3, s3, s92
	s_addc_u32 s43, s83, 0
	s_mov_b32 s33, 1
	v_mov_b32_e32 v16, 0
	s_branch .LBB0_417

; __device__ __forceinline__ unsigned xb_ld(unsigned* p)              { return __hip_atomic_load(p, __ATOMIC_RELAXED, __HIP_MEMORY_SCOPE_AGENT); }
; __device__ __forceinline__ unsigned xb_add(unsigned* p, unsigned v) { return __hip_atomic_fetch_add(p, v, __ATOMIC_RELAXED, __HIP_MEMORY_SCOPE_AGENT); }
; #define XB_SPIN(cond, bar) do { unsigned _sp = 0; while (cond) { __builtin_amdgcn_s_sleep(1); \
;     if ((++_sp & 255u) == 0u) { if (xb_ld(&(bar)[XB_TMO])) break; if (_sp > XB_SPIN_CAP) { atomicAdd(&(bar)[XB_TMO], 1u); break; } } } } while (0)
; __device__ __forceinline__ void xcd_barrier(const XcdBarrier& b) {
;     asm volatile("s_waitcnt vmcnt(0)" ::: "memory");
;     __syncthreads();
;     if (threadIdx.x == 0) {
;         unsigned* bar = b.bar;
;         __builtin_amdgcn_s_waitcnt(0);
;         unsigned nloc = b.st[0], nx = b.st[1];
;         if (nloc == 0u) { xcd_barrier_complete(bar, b.x, nloc, nx); b.st[0] = nloc; b.st[1] = nx; }
;         const unsigned old = xb_add(&bar[XB_XSUB(b.x)], 1u);
;         const unsigned gen = old / nloc;
;         if (old + 1u == (gen + 1u) * nloc) {
;             __builtin_amdgcn_fence(__ATOMIC_RELEASE, "agent");
;             asm volatile("s_waitcnt vmcnt(0)" ::: "memory");
;             const unsigned og = xb_add(&bar[XB_TOP], 1u);
;             const unsigned tg = og / nx;
;             if (og + 1u == (tg + 1u) * nx) xb_add(&bar[XB_TOPGEN], 1u);
;             else XB_SPIN(xb_ld(&bar[XB_TOPGEN]) == tg, bar);
;             __builtin_amdgcn_fence(__ATOMIC_ACQUIRE, "agent");
;             xb_add(&bar[XB_XGEN(b.x)], 1u);
; __global__ void __launch_bounds__(512) fwd_kernel(Params p_unused) {
;     ...
;     xcd_barrier(xb);
.LBB0_470:
	s_or_b64 exec, exec, s[0:1]
	s_waitcnt vmcnt(0)
	s_barrier
	s_mov_b64 s[0:1], exec
	v_readlane_b32 s4, v252, 6
	v_readlane_b32 s5, v252, 7
	s_and_b64 s[4:5], s[0:1], s[4:5]
	s_mov_b64 exec, s[4:5]
	s_cbranch_execz .LBB0_522
	s_waitcnt vmcnt(0) expcnt(0) lgkmcnt(0)
	buffer_inv sc1
	v_mov_b32_e32 v0, 0x23fc0
	ds_read_b32 v2, v0
	ds_read_b32 v3, v0 offset:4
	v_readlane_b32 s3, v252, 5
	s_lshl_b32 s8, s3, 8
	v_mov_b32_e32 v1, 1
	s_add_i32 s23, s8, 0x1000
	v_mov_b32_e32 v4, s23
	global_atomic_add v6, v4, v1, s[84:85] offset:1024 sc0
	s_waitcnt vmcnt(0) lgkmcnt(0)
	v_readfirstlane_b32 s9, v6
	v_readfirstlane_b32 s11, v2
	v_readfirstlane_b32 s22, v3
	s_mul_i32 s11, s11, 5
	s_mul_i32 s22, s22, 5
	s_add_i32 s9, s9, 1
	v_mov_b32_e32 v4, 0x3000
	s_mov_b32 s24, 0
	s_cmp_eq_u32 s9, s11
	s_cbranch_scc0 .Lgb4_poll
	buffer_wbl2 sc1
	s_waitcnt vmcnt(0)
	global_atomic_add v4, v1, s[84:85] offset:1024

; __device__ __forceinline__ void xcd_barrier(const XcdBarrier& b) {
;     asm volatile("s_waitcnt vmcnt(0)" ::: "memory");
;     __syncthreads();
;     if (threadIdx.x == 0) {
;         unsigned* bar = b.bar;
;         __builtin_amdgcn_s_waitcnt(0);
;         unsigned nloc = b.st[0], nx = b.st[1];
;         if (nloc == 0u) { xcd_barrier_complete(bar, b.x, nloc, nx); b.st[0] = nloc; b.st[1] = nx; }
.Lgb4_fin:
	s_waitcnt vmcnt(0) lgkmcnt(0)
	s_branch .LBB0_522
	s_add_i32 s3, 0, 0x23fc0
	v_mov_b32_e32 v0, s3
	s_waitcnt vmcnt(0) expcnt(0) lgkmcnt(0)
	ds_read_b32 v2, v0
	s_add_i32 s3, 0, 0x23fc4
	v_mov_b32_e32 v0, s3
	ds_read_b32 v0, v0
	s_waitcnt lgkmcnt(1)
	v_cmp_ne_u32_e32 vcc, 0, v2
	s_cbranch_vccnz .LBB0_486
	s_add_u32 s4, s82, 0x38a00200
	s_addc_u32 s5, s83, 0
	s_add_u32 s8, s82, 0x38a00400
	s_addc_u32 s9, s83, 0
	s_add_u32 s10, s82, 0x38a00500
	s_addc_u32 s11, s83, 0
	s_add_u32 s12, s82, 0x38a00600
	s_addc_u32 s13, s83, 0
	s_add_u32 s14, s82, 0x38a00700
	s_addc_u32 s15, s83, 0
	s_add_u32 s16, s82, 0x38a00800
	s_addc_u32 s17, s83, 0
	s_add_u32 s18, s82, 0x38a00900
	s_addc_u32 s19, s83, 0
	s_add_u32 s20, s82, 0x38a00a00
	s_addc_u32 s21, s83, 0
	s_add_u32 s22, s82, 0x38a00b00
	s_addc_u32 s23, s83, 0
	s_add_u32 s24, s82, 0x38a00c00
	s_addc_u32 s25, s83, 0
	s_add_u32 s26, s82, 0x38a00d00
	s_addc_u32 s27, s83, 0
	s_add_u32 s28, s82, 0x38a00e00
	s_addc_u32 s29, s83, 0
	s_add_u32 s30, s82, 0x38a00f00
	s_addc_u32 s31, s83, 0
	s_add_u32 s34, s82, 0x38a01000
	s_addc_u32 s35, s83, 0
	s_add_u32 s36, s82, 0x38a01100
	s_addc_u32 s37, s83, 0
	s_add_u32 s38, s82, 0x38a01200
	v_readlane_b32 s3, v252, 0
	s_addc_u32 s39, s83, 0
	s_mul_i32 s3, s93, s3
	s_add_u32 s40, s82, 0x38a01300
	s_mul_i32 s3, s3, s92
	s_addc_u32 s41, s83, 0
	s_mov_b32 s33, 1
	v_mov_b32_e32 v16, 0
	s_branch .LBB0_474

; __device__ __forceinline__ unsigned xb_ld(unsigned* p)              { return __hip_atomic_load(p, __ATOMIC_RELAXED, __HIP_MEMORY_SCOPE_AGENT); }
; __device__ __forceinline__ unsigned xb_add(unsigned* p, unsigned v) { return __hip_atomic_fetch_add(p, v, __ATOMIC_RELAXED, __HIP_MEMORY_SCOPE_AGENT); }
; #define XB_SPIN(cond, bar) do { unsigned _sp = 0; while (cond) { __builtin_amdgcn_s_sleep(1); \
;     if ((++_sp & 255u) == 0u) { if (xb_ld(&(bar)[XB_TMO])) break; if (_sp > XB_SPIN_CAP) { atomicAdd(&(bar)[XB_TMO], 1u); break; } } } } while (0)
; __device__ __forceinline__ void xcd_barrier(const XcdBarrier& b) {
;     asm volatile("s_waitcnt vmcnt(0)" ::: "memory");
;     __syncthreads();
;     if (threadIdx.x == 0) {
;         unsigned* bar = b.bar;
;         __builtin_amdgcn_s_waitcnt(0);
;         unsigned nloc = b.st[0], nx = b.st[1];
;         if (nloc == 0u) { xcd_barrier_complete(bar, b.x, nloc, nx); b.st[0] = nloc; b.st[1] = nx; }
;         const unsigned old = xb_add(&bar[XB_XSUB(b.x)], 1u);
;         const unsigned gen = old / nloc;
;         if (old + 1u == (gen + 1u) * nloc) {
;             __builtin_amdgcn_fence(__ATOMIC_RELEASE, "agent");
;             asm volatile("s_waitcnt vmcnt(0)" ::: "memory");
;             const unsigned og = xb_add(&bar[XB_TOP], 1u);
;             const unsigned tg = og / nx;
;             if (og + 1u == (tg + 1u) * nx) xb_add(&bar[XB_TOPGEN], 1u);
;             else XB_SPIN(xb_ld(&bar[XB_TOPGEN]) == tg, bar);
;             __builtin_amdgcn_fence(__ATOMIC_ACQUIRE, "agent");
;             xb_add(&bar[XB_XGEN(b.x)], 1u);
; __global__ void __launch_bounds__(512) fwd_kernel(Params p_unused) {
;     ...
;     xcd_barrier(xb);
.LBB0_549:
	s_waitcnt vmcnt(0)
	s_barrier
	s_mov_b64 s[0:1], exec
	v_readlane_b32 s4, v252, 6
	v_readlane_b32 s5, v252, 7
	v_readlane_b32 s66, v252, 10
	s_and_b64 s[4:5], s[0:1], s[4:5]
	v_readlane_b32 s67, v252, 11
	s_mov_b64 exec, s[4:5]
	s_cbranch_execz .LBB0_601
	s_waitcnt vmcnt(0) expcnt(0) lgkmcnt(0)
	buffer_inv sc1
	v_mov_b32_e32 v0, 0x23fc0
	ds_read_b32 v2, v0
	ds_read_b32 v3, v0 offset:4
	v_readlane_b32 s3, v252, 5
	s_lshl_b32 s8, s3, 8
	v_mov_b32_e32 v1, 1
	s_add_i32 s23, s8, 0x1000
	v_mov_b32_e32 v4, s23
	global_atomic_add v6, v4, v1, s[84:85] offset:1024 sc0
	s_waitcnt vmcnt(0) lgkmcnt(0)
	v_readfirstlane_b32 s9, v6
	v_readfirstlane_b32 s11, v2
	v_readfirstlane_b32 s22, v3
	s_mul_i32 s11, s11, 6
	s_mul_i32 s22, s22, 6
	s_add_i32 s9, s9, 1
	v_mov_b32_e32 v4, 0x3000
	s_mov_b32 s24, 0
	s_cmp_eq_u32 s9, s11
	s_cbranch_scc0 .Lgb5_poll
	buffer_wbl2 sc1
	s_waitcnt vmcnt(0)
	global_atomic_add v4, v1, s[84:85] offset:1024

; __device__ __forceinline__ void xcd_barrier(const XcdBarrier& b) {
;     asm volatile("s_waitcnt vmcnt(0)" ::: "memory");
;     __syncthreads();
;     if (threadIdx.x == 0) {
;         unsigned* bar = b.bar;
;         __builtin_amdgcn_s_waitcnt(0);
;         unsigned nloc = b.st[0], nx = b.st[1];
;         if (nloc == 0u) { xcd_barrier_complete(bar, b.x, nloc, nx); b.st[0] = nloc; b.st[1] = nx; }
.Lgb5_fin:
	s_waitcnt vmcnt(0) lgkmcnt(0)
	s_branch .LBB0_601
	s_add_i32 s3, 0, 0x23fc0
	v_mov_b32_e32 v0, s3
	s_waitcnt vmcnt(0) expcnt(0) lgkmcnt(0)
	ds_read_b32 v2, v0
	s_add_i32 s3, 0, 0x23fc4
	v_mov_b32_e32 v0, s3
	ds_read_b32 v0, v0
	s_waitcnt lgkmcnt(1)
	v_cmp_ne_u32_e32 vcc, 0, v2
	s_cbranch_vccnz .LBB0_565
	s_add_u32 s4, s66, 0x38a00200
	s_addc_u32 s5, s67, 0
	s_add_u32 s6, s66, 0x38a00400
	s_addc_u32 s7, s67, 0
	s_add_u32 s8, s66, 0x38a00500
	s_addc_u32 s9, s67, 0
	s_add_u32 s10, s66, 0x38a00600
	s_addc_u32 s11, s67, 0
	s_add_u32 s12, s66, 0x38a00700
	s_addc_u32 s13, s67, 0
	s_add_u32 s14, s66, 0x38a00800
	s_addc_u32 s15, s67, 0
	s_add_u32 s16, s66, 0x38a00900
	s_addc_u32 s17, s67, 0
	s_add_u32 s18, s66, 0x38a00a00
	s_addc_u32 s19, s67, 0
	s_add_u32 s20, s66, 0x38a00b00
	s_addc_u32 s21, s67, 0
	s_add_u32 s22, s66, 0x38a00c00
	s_addc_u32 s23, s67, 0
	s_add_u32 s24, s66, 0x38a00d00
	s_addc_u32 s25, s67, 0
	s_add_u32 s26, s66, 0x38a00e00
	s_addc_u32 s27, s67, 0
	s_add_u32 s28, s66, 0x38a00f00
	s_addc_u32 s29, s67, 0
	s_add_u32 s30, s66, 0x38a01000
	s_addc_u32 s31, s67, 0
	s_add_u32 s34, s66, 0x38a01100
	s_addc_u32 s35, s67, 0
	s_add_u32 s36, s66, 0x38a01200
	v_readlane_b32 s3, v252, 0
	s_addc_u32 s37, s67, 0
	s_mul_i32 s3, s93, s3
	s_add_u32 s38, s66, 0x38a01300
	s_mul_i32 s3, s3, s92
	s_addc_u32 s39, s67, 0
	s_mov_b32 s33, 1
	v_mov_b32_e32 v16, 0
	s_branch .LBB0_553

; __device__ __forceinline__ void attn_merge_rms(const Params& p, int row, bfu* dst, int lane) {
;     ...
;     const float* gam = p.attn_g;
;     float g0[8], g1[8]; ld8f32(gam + lane * 8, g0); ld8f32(gam + 512 + lane * 8, g1);
; __device__ __forceinline__ void phase6(const Params& p, int bid, int G) {
;     const int lane = threadIdx.x & 63, wave = threadIdx.x >> 6;
;     const bfu* att = (const bfu*)(p.ws + WS_ATT); const bfu* yg = (const bfu*)(p.ws + WS_YG); bfu* mix = (bfu*)(p.ws + WS_MIX);
;     for (int row = bid * 8 + wave; row < MT; row += G * 8) {
;         if (row < MP) attn_merge_rms(p, row, mix + (size_t)row * 2048, lane);
;         else rms_half(att + (size_t)row * 1024, p.attn_g, mix + (size_t)row * 2048, lane);
;         rms_half(yg + (size_t)row * 1024, p.ssm_g, mix + (size_t)row * 2048 + 1024, lane);
.LBB0_600:
	s_or_b64 exec, exec, s[8:9]
	s_waitcnt vmcnt(0)
.LBB0_601:
	s_or_b64 exec, exec, s[0:1]
	s_lshl_b32 s58, s2, 3
	v_readlane_b32 s8, v252, 1
	v_add_u32_e32 v128, s58, v194
	s_movk_i32 s0, 0x4100
	v_readlane_b32 s9, v252, 2
	v_cmp_gt_i32_e64 s[6:7], s0, v128
	v_ashrrev_i32_e32 v129, 31, v128
	s_waitcnt lgkmcnt(0)
	s_barrier
	s_and_saveexec_b64 s[0:1], s[6:7]
	s_cbranch_execz .LBB0_608
	v_mbcnt_lo_u32_b32 v0, -1, 0
	v_mbcnt_hi_u32_b32 v0, -1, v0
	v_and_b32_e32 v2, 64, v0
	v_xor_b32_e32 v1, 32, v0
	v_add_u32_e32 v2, 64, v2
	v_cmp_lt_i32_e32 vcc, v1, v2
	s_load_dwordx2 s[4:5], s[8:9], 0xb8
	s_load_dwordx4 s[12:15], s[8:9], 0x60
	v_cndmask_b32_e32 v1, v0, v1, vcc
	v_lshlrev_b32_e32 v40, 2, v1
	v_xor_b32_e32 v1, 16, v0
	v_cmp_lt_i32_e32 vcc, v1, v2
	s_mov_b64 s[8:9], 0x1a900000
	s_lshl_b32 s10, s92, 3
	v_cndmask_b32_e32 v1, v0, v1, vcc
	v_lshlrev_b32_e32 v41, 2, v1
	v_xor_b32_e32 v1, 8, v0
	v_cmp_lt_i32_e32 vcc, v1, v2
	s_ashr_i32 s11, s10, 31
	v_lshlrev_b64 v[12:13], 11, v[128:129]
	v_cndmask_b32_e32 v1, v0, v1, vcc
	v_lshlrev_b32_e32 v42, 2, v1
	v_xor_b32_e32 v1, 4, v0
	v_cmp_lt_i32_e32 vcc, v1, v2
	v_lshlrev_b64 v[16:17], 6, v[128:129]
	v_mov_b32_e32 v15, v13
	v_cndmask_b32_e32 v1, v0, v1, vcc
	v_lshlrev_b32_e32 v43, 2, v1
	v_xor_b32_e32 v1, 2, v0
	v_cmp_lt_i32_e32 vcc, v1, v2
	v_and_or_b32 v16, v177, 28, v16
	s_mov_b64 s[16:17], 0
	v_cndmask_b32_e32 v1, v0, v1, vcc
	v_lshlrev_b32_e32 v44, 2, v1
	v_xor_b32_e32 v1, 1, v0
	v_cmp_lt_i32_e32 vcc, v1, v2
	s_movk_i32 s3, 0x3fff
	v_mov_b32_e32 v46, 0x3727c5ac
	v_cndmask_b32_e32 v0, v0, v1, vcc
	v_lshlrev_b32_e32 v45, 2, v0
	v_lshlrev_b32_e32 v0, 5, v179
	v_mov_b32_e32 v1, 0
	s_waitcnt lgkmcnt(0)
	v_lshl_add_u64 v[2:3], s[14:15], 0, v[0:1]
	v_lshl_add_u64 v[4:5], s[12:13], 0, v[0:1]
	v_lshlrev_b32_e32 v0, 4, v179
	v_lshl_add_u64 v[10:11], s[4:5], 0, v[0:1]
	v_lshl_add_u64 v[6:7], v[10:11], 0, s[8:9]
	s_mov_b64 s[8:9], 0x24c00000
	v_lshl_add_u64 v[8:9], v[10:11], 0, s[8:9]
	s_mov_b64 s[8:9], 0x22b00000
	v_lshl_add_u64 v[10:11], v[10:11], 0, s[8:9]
	v_or_b32_e32 v14, v12, v0
	s_lshl_b64 s[12:13], s[10:11], 11
	s_lshl_b64 s[14:15], s[10:11], 6
	s_mov_b32 s20, 0x800000
	s_mov_b32 s21, 0x28d00000
	s_mov_b32 s22, 0x2ad00000
	s_mov_b32 s23, 0x2cd00000
	s_movk_i32 s24, 0x40ff
	v_mov_b64_e32 v[18:19], v[128:129]
	global_load_dwordx4 v[104:107], v[4:5], off offset:2064
	global_load_dwordx4 v[108:111], v[4:5], off offset:2048
	global_load_dwordx4 v[112:115], v[4:5], off offset:16
	global_load_dwordx4 v[116:119], v[4:5], off
	global_load_dwordx4 v[130:133], v[2:3], off offset:2064
	global_load_dwordx4 v[134:137], v[2:3], off offset:2048
	global_load_dwordx4 v[138:141], v[2:3], off offset:16
	global_load_dwordx4 v[142:145], v[2:3], off
	s_branch .LBB0_604

; __device__ __forceinline__ unsigned xb_ld(unsigned* p)              { return __hip_atomic_load(p, __ATOMIC_RELAXED, __HIP_MEMORY_SCOPE_AGENT); }
; __device__ __forceinline__ unsigned xb_add(unsigned* p, unsigned v) { return __hip_atomic_fetch_add(p, v, __ATOMIC_RELAXED, __HIP_MEMORY_SCOPE_AGENT); }
; #define XB_SPIN(cond, bar) do { unsigned _sp = 0; while (cond) { __builtin_amdgcn_s_sleep(1); \
;     if ((++_sp & 255u) == 0u) { if (xb_ld(&(bar)[XB_TMO])) break; if (_sp > XB_SPIN_CAP) { atomicAdd(&(bar)[XB_TMO], 1u); break; } } } } while (0)
; __device__ __forceinline__ void xcd_barrier(const XcdBarrier& b) {
;     asm volatile("s_waitcnt vmcnt(0)" ::: "memory");
;     __syncthreads();
;     if (threadIdx.x == 0) {
;         unsigned* bar = b.bar;
;         __builtin_amdgcn_s_waitcnt(0);
;         unsigned nloc = b.st[0], nx = b.st[1];
;         if (nloc == 0u) { xcd_barrier_complete(bar, b.x, nloc, nx); b.st[0] = nloc; b.st[1] = nx; }
;         const unsigned old = xb_add(&bar[XB_XSUB(b.x)], 1u);
;         const unsigned gen = old / nloc;
;         if (old + 1u == (gen + 1u) * nloc) {
;             __builtin_amdgcn_fence(__ATOMIC_RELEASE, "agent");
;             asm volatile("s_waitcnt vmcnt(0)" ::: "memory");
;             const unsigned og = xb_add(&bar[XB_TOP], 1u);
;             const unsigned tg = og / nx;
;             if (og + 1u == (tg + 1u) * nx) xb_add(&bar[XB_TOPGEN], 1u);
;             else XB_SPIN(xb_ld(&bar[XB_TOPGEN]) == tg, bar);
;             __builtin_amdgcn_fence(__ATOMIC_ACQUIRE, "agent");
;             xb_add(&bar[XB_XGEN(b.x)], 1u);
; __global__ void __launch_bounds__(512) fwd_kernel(Params p_unused) {
;     ...
;     xcd_barrier(xb);
.LBB0_608:
	s_or_b64 exec, exec, s[0:1]
	s_waitcnt vmcnt(0)
	s_barrier
	s_mov_b64 s[0:1], exec
	v_readlane_b32 s4, v252, 6
	v_readlane_b32 s5, v252, 7
	s_and_b64 s[4:5], s[0:1], s[4:5]
	s_mov_b64 exec, s[4:5]
	s_cbranch_execz .LBB0_660
	s_waitcnt vmcnt(0) expcnt(0) lgkmcnt(0)
	buffer_inv sc1
	v_mov_b32_e32 v0, 0x23fc0
	ds_read_b32 v2, v0
	ds_read_b32 v3, v0 offset:4
	v_readlane_b32 s3, v252, 5
	s_lshl_b32 s8, s3, 8
	v_mov_b32_e32 v1, 1
	s_add_i32 s23, s8, 0x1000
	v_mov_b32_e32 v4, s23
	global_atomic_add v6, v4, v1, s[84:85] offset:1024 sc0
	s_waitcnt vmcnt(0) lgkmcnt(0)
	v_readfirstlane_b32 s9, v6
	v_readfirstlane_b32 s11, v2
	v_readfirstlane_b32 s22, v3
	s_mul_i32 s11, s11, 7
	s_mul_i32 s22, s22, 7
	s_add_i32 s9, s9, 1
	v_mov_b32_e32 v4, 0x3000
	s_mov_b32 s24, 0
	s_cmp_eq_u32 s9, s11
	s_cbranch_scc0 .Lgb6_poll
	buffer_wbl2 sc1
	s_waitcnt vmcnt(0)
	global_atomic_add v4, v1, s[84:85] offset:1024

; __device__ __forceinline__ void xcd_barrier(const XcdBarrier& b) {
;     asm volatile("s_waitcnt vmcnt(0)" ::: "memory");
;     __syncthreads();
;     if (threadIdx.x == 0) {
;         unsigned* bar = b.bar;
;         __builtin_amdgcn_s_waitcnt(0);
;         unsigned nloc = b.st[0], nx = b.st[1];
;         if (nloc == 0u) { xcd_barrier_complete(bar, b.x, nloc, nx); b.st[0] = nloc; b.st[1] = nx; }
.Lgb6_fin:
	s_waitcnt vmcnt(0) lgkmcnt(0)
	s_branch .LBB0_660
	s_add_i32 s3, 0, 0x23fc0
	v_mov_b32_e32 v0, s3
	s_waitcnt vmcnt(0) expcnt(0) lgkmcnt(0)
	ds_read_b32 v2, v0
	s_add_i32 s3, 0, 0x23fc4
	v_mov_b32_e32 v0, s3
	ds_read_b32 v0, v0
	s_waitcnt lgkmcnt(1)
	v_cmp_ne_u32_e32 vcc, 0, v2
	s_cbranch_vccnz .LBB0_624
	s_add_u32 s4, s66, 0x38a00200
	s_addc_u32 s5, s67, 0
	s_add_u32 s8, s66, 0x38a00400
	s_addc_u32 s9, s67, 0
	s_add_u32 s10, s66, 0x38a00500
	s_addc_u32 s11, s67, 0
	s_add_u32 s12, s66, 0x38a00600
	s_addc_u32 s13, s67, 0
	s_add_u32 s14, s66, 0x38a00700
	s_addc_u32 s15, s67, 0
	s_add_u32 s16, s66, 0x38a00800
	s_addc_u32 s17, s67, 0
	s_add_u32 s18, s66, 0x38a00900
	s_addc_u32 s19, s67, 0
	s_add_u32 s20, s66, 0x38a00a00
	s_addc_u32 s21, s67, 0
	s_add_u32 s22, s66, 0x38a00b00
	s_addc_u32 s23, s67, 0
	s_add_u32 s24, s66, 0x38a00c00
	s_addc_u32 s25, s67, 0
	s_add_u32 s26, s66, 0x38a00d00
	s_addc_u32 s27, s67, 0
	s_add_u32 s28, s66, 0x38a00e00
	s_addc_u32 s29, s67, 0
	s_add_u32 s30, s66, 0x38a00f00
	s_addc_u32 s31, s67, 0
	s_add_u32 s34, s66, 0x38a01000
	s_addc_u32 s35, s67, 0
	s_add_u32 s36, s66, 0x38a01100
	s_addc_u32 s37, s67, 0
	s_add_u32 s38, s66, 0x38a01200
	v_readlane_b32 s3, v252, 0
	s_addc_u32 s39, s67, 0
	s_mul_i32 s3, s93, s3
	s_add_u32 s40, s66, 0x38a01300
	s_mul_i32 s3, s3, s92
	s_addc_u32 s41, s67, 0
	s_mov_b32 s33, 1
	v_mov_b32_e32 v16, 0
	s_branch .LBB0_612

; __device__ __forceinline__ unsigned xb_ld(unsigned* p)              { return __hip_atomic_load(p, __ATOMIC_RELAXED, __HIP_MEMORY_SCOPE_AGENT); }
; __device__ __forceinline__ unsigned xb_add(unsigned* p, unsigned v) { return __hip_atomic_fetch_add(p, v, __ATOMIC_RELAXED, __HIP_MEMORY_SCOPE_AGENT); }
; #define XB_SPIN(cond, bar) do { unsigned _sp = 0; while (cond) { __builtin_amdgcn_s_sleep(1); \
;     if ((++_sp & 255u) == 0u) { if (xb_ld(&(bar)[XB_TMO])) break; if (_sp > XB_SPIN_CAP) { atomicAdd(&(bar)[XB_TMO], 1u); break; } } } } while (0)
; __device__ __forceinline__ void xcd_barrier(const XcdBarrier& b) {
;     asm volatile("s_waitcnt vmcnt(0)" ::: "memory");
;     __syncthreads();
;     if (threadIdx.x == 0) {
;         unsigned* bar = b.bar;
;         __builtin_amdgcn_s_waitcnt(0);
;         unsigned nloc = b.st[0], nx = b.st[1];
;         if (nloc == 0u) { xcd_barrier_complete(bar, b.x, nloc, nx); b.st[0] = nloc; b.st[1] = nx; }
;         const unsigned old = xb_add(&bar[XB_XSUB(b.x)], 1u);
;         const unsigned gen = old / nloc;
;         if (old + 1u == (gen + 1u) * nloc) {
;             __builtin_amdgcn_fence(__ATOMIC_RELEASE, "agent");
;             asm volatile("s_waitcnt vmcnt(0)" ::: "memory");
;             const unsigned og = xb_add(&bar[XB_TOP], 1u);
;             const unsigned tg = og / nx;
;             if (og + 1u == (tg + 1u) * nx) xb_add(&bar[XB_TOPGEN], 1u);
;             else XB_SPIN(xb_ld(&bar[XB_TOPGEN]) == tg, bar);
;             __builtin_amdgcn_fence(__ATOMIC_ACQUIRE, "agent");
;             xb_add(&bar[XB_XGEN(b.x)], 1u);
; __global__ void __launch_bounds__(512) fwd_kernel(Params p_unused) {
;     ...
;         xcd_barrier(xb);
.LBB0_1087:
	s_waitcnt vmcnt(0)
	s_mov_b64 s[0:1], 0x4000000
	s_barrier
	s_mov_b64 s[4:5], exec
	v_readlane_b32 s6, v252, 6
	v_readlane_b32 s7, v252, 7
	s_and_b64 s[6:7], s[4:5], s[6:7]
	s_mov_b64 exec, s[6:7]
	s_cbranch_execz .LBB0_1139
	s_waitcnt vmcnt(0) expcnt(0) lgkmcnt(0)
	buffer_inv sc1
	v_mov_b32_e32 v0, 0x23fc0
	ds_read_b32 v2, v0
	ds_read_b32 v3, v0 offset:4
	v_readlane_b32 s3, v252, 5
	s_lshl_b32 s8, s3, 8
	v_mov_b32_e32 v1, 1
	s_add_i32 s23, s8, 0x1000
	v_mov_b32_e32 v4, s23
	global_atomic_add v6, v4, v1, s[84:85] offset:1024 sc0
	s_waitcnt vmcnt(0) lgkmcnt(0)
	v_readfirstlane_b32 s9, v6
	v_readfirstlane_b32 s11, v2
	v_readfirstlane_b32 s22, v3
	s_mul_i32 s11, s11, 8
	s_mul_i32 s22, s22, 8
	s_add_i32 s9, s9, 1
	v_mov_b32_e32 v4, 0x3000
	s_mov_b32 s24, 0
	s_cmp_eq_u32 s9, s11
	s_cbranch_scc0 .Lgb7_poll
	buffer_wbl2 sc1
	s_waitcnt vmcnt(0)
	global_atomic_add v4, v1, s[84:85] offset:1024

; __device__ __forceinline__ void xcd_barrier(const XcdBarrier& b) {
;     asm volatile("s_waitcnt vmcnt(0)" ::: "memory");
;     __syncthreads();
;     if (threadIdx.x == 0) {
;         unsigned* bar = b.bar;
;         __builtin_amdgcn_s_waitcnt(0);
;         unsigned nloc = b.st[0], nx = b.st[1];
;         if (nloc == 0u) { xcd_barrier_complete(bar, b.x, nloc, nx); b.st[0] = nloc; b.st[1] = nx; }
.Lgb7_fin:
	s_waitcnt vmcnt(0) lgkmcnt(0)
	s_branch .LBB0_1139
	s_add_i32 s3, 0, 0x23fc0
	v_mov_b32_e32 v0, s3
	s_waitcnt vmcnt(0) expcnt(0) lgkmcnt(0)
	ds_read_b32 v2, v0
	s_add_i32 s3, 0, 0x23fc4
	v_mov_b32_e32 v0, s3
	ds_read_b32 v0, v0
	s_waitcnt lgkmcnt(1)
	v_cmp_ne_u32_e32 vcc, 0, v2
	s_cbranch_vccnz .LBB0_1103
	v_readlane_b32 s3, v252, 0
	s_mul_i32 s3, s93, s3
	s_lshl_b32 s3, s3, 8
	s_add_u32 s6, s66, 0x38a00200
	s_addc_u32 s7, s67, 0
	s_add_u32 s8, s66, 0x38a00400
	s_addc_u32 s9, s67, 0
	s_add_u32 s20, s66, 0x38a00500
	s_addc_u32 s21, s67, 0
	s_add_u32 s22, s66, 0x38a00600
	s_addc_u32 s23, s67, 0
	s_add_u32 s24, s66, 0x38a00700
	s_addc_u32 s25, s67, 0
	s_add_u32 s26, s66, 0x38a00800
	s_addc_u32 s27, s67, 0
	s_add_u32 s28, s66, 0x38a00900
	s_addc_u32 s29, s67, 0
	s_add_u32 s30, s66, 0x38a00a00
	s_addc_u32 s31, s67, 0
	s_add_u32 s34, s66, 0x38a00b00
	s_addc_u32 s35, s67, 0
	s_add_u32 s36, s66, 0x38a00c00
	s_addc_u32 s37, s67, 0
	s_add_u32 s38, s66, 0x38a00d00
	s_addc_u32 s39, s67, 0
	s_add_u32 s40, s66, 0x38a00e00
	s_addc_u32 s41, s67, 0
	s_add_u32 s42, s66, 0x38a00f00
	s_addc_u32 s43, s67, 0
	s_add_u32 s44, s66, 0x38a01000
	s_addc_u32 s45, s67, 0
	s_add_u32 s46, s66, 0x38a01100
	s_addc_u32 s47, s67, 0
	s_add_u32 s48, s66, 0x38a01200
	s_addc_u32 s49, s67, 0
	s_add_u32 s50, s66, 0x38a01300
	s_addc_u32 s51, s67, 0
	s_mov_b32 s11, 1
	v_mov_b32_e32 v16, 0
	s_branch .LBB0_1091

; __device__ __forceinline__ unsigned xb_ld(unsigned* p)              { return __hip_atomic_load(p, __ATOMIC_RELAXED, __HIP_MEMORY_SCOPE_AGENT); }
; __device__ __forceinline__ unsigned xb_add(unsigned* p, unsigned v) { return __hip_atomic_fetch_add(p, v, __ATOMIC_RELAXED, __HIP_MEMORY_SCOPE_AGENT); }
; #define XB_SPIN(cond, bar) do { unsigned _sp = 0; while (cond) { __builtin_amdgcn_s_sleep(1); \
;     if ((++_sp & 255u) == 0u) { if (xb_ld(&(bar)[XB_TMO])) break; if (_sp > XB_SPIN_CAP) { atomicAdd(&(bar)[XB_TMO], 1u); break; } } } } while (0)
; __device__ __forceinline__ void xcd_barrier(const XcdBarrier& b) {
;     asm volatile("s_waitcnt vmcnt(0)" ::: "memory");
;     __syncthreads();
;     if (threadIdx.x == 0) {
;         unsigned* bar = b.bar;
;         __builtin_amdgcn_s_waitcnt(0);
;         unsigned nloc = b.st[0], nx = b.st[1];
;         if (nloc == 0u) { xcd_barrier_complete(bar, b.x, nloc, nx); b.st[0] = nloc; b.st[1] = nx; }
;         const unsigned old = xb_add(&bar[XB_XSUB(b.x)], 1u);
;         const unsigned gen = old / nloc;
;         if (old + 1u == (gen + 1u) * nloc) {
;             __builtin_amdgcn_fence(__ATOMIC_RELEASE, "agent");
;             asm volatile("s_waitcnt vmcnt(0)" ::: "memory");
;             const unsigned og = xb_add(&bar[XB_TOP], 1u);
;             const unsigned tg = og / nx;
;             if (og + 1u == (tg + 1u) * nx) xb_add(&bar[XB_TOPGEN], 1u);
;             else XB_SPIN(xb_ld(&bar[XB_TOPGEN]) == tg, bar);
;             __builtin_amdgcn_fence(__ATOMIC_ACQUIRE, "agent");
;             xb_add(&bar[XB_XGEN(b.x)], 1u);
; __global__ void __launch_bounds__(512) fwd_kernel(Params p_unused) {
;     ...
;         xcd_barrier(xb);
.LBB0_1174:
	s_waitcnt vmcnt(0)
	s_waitcnt vmcnt(0)
	s_barrier
	s_mov_b64 s[0:1], exec
	v_readlane_b32 s4, v252, 6
	v_readlane_b32 s5, v252, 7
	s_and_b64 s[4:5], s[0:1], s[4:5]
	s_mov_b64 exec, s[4:5]
	s_cbranch_execz .LBB0_1226
	s_waitcnt vmcnt(0) expcnt(0) lgkmcnt(0)
	buffer_inv sc1
	v_mov_b32_e32 v0, 0x23fc0
	ds_read_b32 v2, v0
	ds_read_b32 v3, v0 offset:4
	v_readlane_b32 s3, v252, 5
	s_lshl_b32 s8, s3, 8
	v_mov_b32_e32 v1, 1
	s_add_i32 s23, s8, 0x1000
	v_mov_b32_e32 v4, s23
	global_atomic_add v6, v4, v1, s[84:85] offset:1024 sc0
	s_waitcnt vmcnt(0) lgkmcnt(0)
	v_readfirstlane_b32 s9, v6
	v_readfirstlane_b32 s11, v2
	v_readfirstlane_b32 s22, v3
	s_mul_i32 s11, s11, 9
	s_mul_i32 s22, s22, 9
	s_add_i32 s9, s9, 1
	v_mov_b32_e32 v4, 0x3000
	s_mov_b32 s24, 0
	s_cmp_eq_u32 s9, s11
	s_cbranch_scc0 .Lgb8_poll
	buffer_wbl2 sc1
	s_waitcnt vmcnt(0)
	global_atomic_add v4, v1, s[84:85] offset:1024

; __device__ __forceinline__ void xcd_barrier(const XcdBarrier& b) {
;     asm volatile("s_waitcnt vmcnt(0)" ::: "memory");
;     __syncthreads();
;     if (threadIdx.x == 0) {
;         unsigned* bar = b.bar;
;         __builtin_amdgcn_s_waitcnt(0);
;         unsigned nloc = b.st[0], nx = b.st[1];
;         if (nloc == 0u) { xcd_barrier_complete(bar, b.x, nloc, nx); b.st[0] = nloc; b.st[1] = nx; }
.Lgb8_fin:
	s_waitcnt vmcnt(0) lgkmcnt(0)
	s_branch .LBB0_1226
	s_add_i32 s3, 0, 0x23fc0
	v_mov_b32_e32 v0, s3
	s_waitcnt vmcnt(0) expcnt(0) lgkmcnt(0)
	ds_read_b32 v2, v0
	s_add_i32 s3, 0, 0x23fc4
	v_mov_b32_e32 v0, s3
	ds_read_b32 v0, v0
	s_waitcnt lgkmcnt(1)
	v_cmp_ne_u32_e32 vcc, 0, v2
	s_cbranch_vccnz .LBB0_1190
	v_readlane_b32 s3, v252, 0
	s_mul_i32 s3, s93, s3
	s_lshl_b32 s3, s3, 8
	s_add_u32 s4, s66, 0x38a00200
	s_addc_u32 s5, s67, 0
	s_add_u32 s6, s66, 0x38a00400
	s_addc_u32 s7, s67, 0
	s_add_u32 s8, s66, 0x38a00500
	s_addc_u32 s9, s67, 0
	s_add_u32 s22, s66, 0x38a00600
	s_addc_u32 s23, s67, 0
	s_add_u32 s24, s66, 0x38a00700
	s_addc_u32 s25, s67, 0
	s_add_u32 s26, s66, 0x38a00800
	s_addc_u32 s27, s67, 0
	s_add_u32 s28, s66, 0x38a00900
	s_addc_u32 s29, s67, 0
	s_add_u32 s30, s66, 0x38a00a00
	s_addc_u32 s31, s67, 0
	s_add_u32 s34, s66, 0x38a00b00
	s_addc_u32 s35, s67, 0
	s_add_u32 s36, s66, 0x38a00c00
	s_addc_u32 s37, s67, 0
	s_add_u32 s38, s66, 0x38a00d00
	s_addc_u32 s39, s67, 0
	s_add_u32 s40, s66, 0x38a00e00
	s_addc_u32 s41, s67, 0
	s_add_u32 s42, s66, 0x38a00f00
	s_addc_u32 s43, s67, 0
	s_add_u32 s44, s66, 0x38a01000
	s_addc_u32 s45, s67, 0
	s_add_u32 s46, s66, 0x38a01100
	s_addc_u32 s47, s67, 0
	s_add_u32 s48, s66, 0x38a01200
	s_addc_u32 s49, s67, 0
	s_add_u32 s50, s66, 0x38a01300
	s_addc_u32 s51, s67, 0
	s_mov_b32 s11, 1
	v_mov_b32_e32 v16, 0
	s_branch .LBB0_1178

; #define MFMA16(a, b, c) __builtin_amdgcn_mfma_f32_16x16x32_bf16((a), (b), (c), 0, 0, 0)
; template <int K>
; __device__ __forceinline__ void skinny_sample_gemm(const bfu* __restrict__ A, const bfu* __restrict__ Bt, const float* __restrict__ res, float* __restrict__ pre, float* ldsf, int bid) {
;     const int tid = threadIdx.x, lane = tid & 63, wave = __builtin_amdgcn_readfirstlane(tid >> 6), l15 = lane & 15, quad = lane >> 4;
;     const int rg = bid >> 4, cg = bid & 15;
;     constexpr int KW = K / 8, NS = KW / 32;
;     const bfu* ap = A + (size_t)(MP + rg * 16 + l15) * K + wave * KW + quad * 8;
;     const bfu* bp = Bt + (size_t)(cg * 64 + l15) * K + wave * KW + quad * 8;
;     f32x4 acc[4];
; #pragma unroll
;     for (int nt = 0; nt < 4; ++nt) acc[nt] = (f32x4){0.f, 0.f, 0.f, 0.f};
; #pragma unroll
;     for (int ks = 0; ks < NS; ++ks) {
;         const bf16x8 af = ld8g(ap + ks * 32);
; #pragma unroll
;         for (int nt = 0; nt < 4; ++nt) acc[nt] = MFMA16(af, ld8g(bp + (size_t)nt * 16 * K + ks * 32), acc[nt]);
;     }
; #pragma unroll
;     for (int nt = 0; nt < 4; ++nt)
; #pragma unroll
;         for (int j = 0; j < 4; ++j) ldsf[wave * 1024 + (quad * 4 + j) * 64 + nt * 16 + l15] = acc[nt][j];
.LBB0_1225:
	s_or_b64 exec, exec, s[8:9]
	s_waitcnt vmcnt(0)
.LBB0_1226:
	s_or_b64 exec, exec, s[0:1]
	s_add_u32 s24, s66, 0x1c00000
	v_readfirstlane_b32 s0, v172
	s_addc_u32 s25, s67, 0
	s_lshr_b32 s0, s0, 6
	s_waitcnt lgkmcnt(0)
	v_mul_u32_u24_e32 v0, 0xb00, v187
	s_mul_i32 s4, s0, 0x160
	s_mov_b32 s5, 0
	v_lshlrev_b32_e32 v44, 1, v0
	v_mov_b32_e32 v45, 0
	v_lshl_add_u64 v[4:5], s[24:25], 0, v[44:45]
	s_lshl_b64 s[4:5], s[4:5], 1
	s_movk_i32 s1, 0x1600
	v_mov_b64_e32 v[0:1], s[20:21]
	v_mad_i64_i32 v[0:1], s[6:7], v134, s1, v[0:1]
	v_lshlrev_b32_e32 v44, 1, v195
	v_lshl_add_u64 v[4:5], v[4:5], 0, s[4:5]
	v_lshl_add_u64 v[0:1], v[0:1], 0, s[4:5]
	v_lshl_add_u64 v[48:49], v[4:5], 0, v[44:45]
	s_mov_b32 s1, 0x16000
	v_lshl_add_u64 v[46:47], v[0:1], 0, v[44:45]
	v_add_co_u32_e32 v50, vcc, s1, v48
	s_barrier
	s_add_u32 s98, s66, s10
	s_addc_u32 s99, s67, 0
	s_add_u32 s98, s98, 0x30e00000
	s_addc_u32 s99, s99, 0
	v_mov_b32_e32 v60, v128
	v_mov_b32_e32 v61, 0
	v_lshl_add_u64 v[60:61], s[98:99], 0, v[60:61]
	v_lshl_add_u64 v[62:63], v[60:61], 0, v[130:131]
	v_lshl_add_u64 v[60:61], v[60:61], 0, v[132:133]
	global_load_dword v64, v[62:63], off
	global_load_dword v65, v[60:61], off
	global_load_dwordx4 v[0:3], v[46:47], off
	global_load_dwordx4 v[4:7], v[48:49], off
	s_mov_b32 s3, 0x2c000
	v_addc_co_u32_e32 v51, vcc, 0, v49, vcc
	v_add_co_u32_e32 v52, vcc, s3, v48
	s_mov_b32 s1, 0x42000
	s_nop 0
	v_addc_co_u32_e32 v53, vcc, 0, v49, vcc
	v_add_co_u32_e32 v54, vcc, s1, v48
	global_load_dwordx4 v[8:11], v[50:51], off
	global_load_dwordx4 v[12:15], v[46:47], off offset:64
	global_load_dwordx4 v[16:19], v[46:47], off offset:640
	global_load_dwordx4 v[20:23], v[52:53], off
	v_addc_co_u32_e32 v55, vcc, 0, v49, vcc
	global_load_dwordx4 v[24:27], v[50:51], off offset:64
	global_load_dwordx4 v[28:31], v[50:51], off offset:640
	global_load_dwordx4 v[32:35], v[54:55], off
	global_load_dwordx4 v[36:39], v[54:55], off offset:64
	s_lshl_b32 s0, s0, 12
	s_add_i32 s0, s0, 0
	v_mov_b32_e32 v129, v45
	s_waitcnt vmcnt(8)
	v_mfma_f32_16x16x32_bf16 v[4:7], v[0:3], v[4:7], 0
	s_waitcnt vmcnt(7)
	v_mfma_f32_16x16x32_bf16 v[8:11], v[0:3], v[8:11], 0
	s_waitcnt vmcnt(4)
	v_mfma_f32_16x16x32_bf16 v[20:23], v[0:3], v[20:23], 0
	s_waitcnt vmcnt(1)
	v_mfma_f32_16x16x32_bf16 v[0:3], v[0:3], v[32:35], 0
	global_load_dwordx4 v[32:35], v[48:49], off offset:64
	global_load_dwordx4 v[40:43], v[48:49], off offset:128
	v_mfma_f32_16x16x32_bf16 v[8:11], v[12:15], v[24:27], v[8:11]
	s_waitcnt vmcnt(2)
	v_mfma_f32_16x16x32_bf16 v[0:3], v[12:15], v[36:39], v[0:3]
	s_waitcnt vmcnt(1)
	v_mfma_f32_16x16x32_bf16 v[4:7], v[12:15], v[32:35], v[4:7]
	global_load_dwordx4 v[24:27], v[52:53], off offset:64
	global_load_dwordx4 v[32:35], v[52:53], off offset:128
	s_waitcnt vmcnt(1)
	v_mfma_f32_16x16x32_bf16 v[20:23], v[12:15], v[24:27], v[20:23]
	global_load_dwordx4 v[12:15], v[46:47], off offset:128
	global_load_dwordx4 v[24:27], v[46:47], off offset:192
	s_waitcnt vmcnt(1)
	v_mfma_f32_16x16x32_bf16 v[4:7], v[12:15], v[40:43], v[4:7]
	global_load_dwordx4 v[36:39], v[50:51], off offset:128
	global_load_dwordx4 v[40:43], v[50:51], off offset:192
	v_mfma_f32_16x16x32_bf16 v[20:23], v[12:15], v[32:35], v[20:23]
	s_waitcnt vmcnt(1)
	v_mfma_f32_16x16x32_bf16 v[8:11], v[12:15], v[36:39], v[8:11]
	global_load_dwordx4 v[32:35], v[54:55], off offset:128
	global_load_dwordx4 v[36:39], v[54:55], off offset:192
	s_waitcnt vmcnt(2)
	v_mfma_f32_16x16x32_bf16 v[8:11], v[24:27], v[40:43], v[8:11]
	s_waitcnt vmcnt(1)
	v_mfma_f32_16x16x32_bf16 v[0:3], v[12:15], v[32:35], v[0:3]
	global_load_dwordx4 v[12:15], v[48:49], off offset:192
	global_load_dwordx4 v[32:35], v[48:49], off offset:256
	s_waitcnt vmcnt(2)
	v_mfma_f32_16x16x32_bf16 v[0:3], v[24:27], v[36:39], v[0:3]
	s_waitcnt vmcnt(1)
	v_mfma_f32_16x16x32_bf16 v[4:7], v[24:27], v[12:15], v[4:7]
	global_load_dwordx4 v[12:15], v[52:53], off offset:192
	global_load_dwordx4 v[40:43], v[52:53], off offset:256
	s_waitcnt vmcnt(1)
	v_mfma_f32_16x16x32_bf16 v[12:15], v[24:27], v[12:15], v[20:23]
	s_nop 2
	global_load_dwordx4 v[20:23], v[46:47], off offset:256
	global_load_dwordx4 v[24:27], v[46:47], off offset:320
	s_waitcnt vmcnt(1)
	v_mfma_f32_16x16x32_bf16 v[4:7], v[20:23], v[32:35], v[4:7]
	global_load_dwordx4 v[32:35], v[50:51], off offset:256
	global_load_dwordx4 v[36:39], v[50:51], off offset:320
	v_mfma_f32_16x16x32_bf16 v[12:15], v[20:23], v[40:43], v[12:15]
	s_waitcnt vmcnt(1)
	v_mfma_f32_16x16x32_bf16 v[8:11], v[20:23], v[32:35], v[8:11]
	global_load_dwordx4 v[32:35], v[54:55], off offset:256
	global_load_dwordx4 v[40:43], v[54:55], off offset:320
	s_waitcnt vmcnt(2)
	v_mfma_f32_16x16x32_bf16 v[8:11], v[24:27], v[36:39], v[8:11]
	s_waitcnt vmcnt(1)
	v_mfma_f32_16x16x32_bf16 v[0:3], v[20:23], v[32:35], v[0:3]
	global_load_dwordx4 v[20:23], v[48:49], off offset:320
	global_load_dwordx4 v[32:35], v[48:49], off offset:384
	s_waitcnt vmcnt(2)
	v_mfma_f32_16x16x32_bf16 v[0:3], v[24:27], v[40:43], v[0:3]
	s_waitcnt vmcnt(1)
; #define MFMA16(a, b, c) __builtin_amdgcn_mfma_f32_16x16x32_bf16((a), (b), (c), 0, 0, 0)
; template <int K>
; __device__ __forceinline__ void skinny_sample_gemm(const bfu* __restrict__ A, const bfu* __restrict__ Bt, const float* __restrict__ res, float* __restrict__ pre, float* ldsf, int bid) {
;     ...
;     for (int ks = 0; ks < NS; ++ks) {
;         const bf16x8 af = ld8g(ap + ks * 32);
; #pragma unroll
;         for (int nt = 0; nt < 4; ++nt) acc[nt] = MFMA16(af, ld8g(bp + (size_t)nt * 16 * K + ks * 32), acc[nt]);
;     }
; #pragma unroll
;     for (int nt = 0; nt < 4; ++nt)
; #pragma unroll
;         for (int j = 0; j < 4; ++j) ldsf[wave * 1024 + (quad * 4 + j) * 64 + nt * 16 + l15] = acc[nt][j];
;     __syncthreads();
; #pragma unroll
;     for (int i = 0; i < 2; ++i) {
;         const int e = tid + 512 * i, r = e >> 6, c = e & 63;
;         float v = 0.f;
; #pragma unroll
;         for (int w = 0; w < 8; ++w) v += ldsf[w * 1024 + e];
;         const size_t row = (size_t)(rg * 16 + r);
;         pre[(MP + row) * 1024 + cg * 64 + c] = v + ALPHA * res[row * 1024 + cg * 64 + c];
;     }
;     __syncthreads();
	v_mfma_f32_16x16x32_bf16 v[4:7], v[24:27], v[20:23], v[4:7]
	global_load_dwordx4 v[20:23], v[52:53], off offset:320
	global_load_dwordx4 v[36:39], v[52:53], off offset:384
	s_waitcnt vmcnt(1)
	v_mfma_f32_16x16x32_bf16 v[12:15], v[24:27], v[20:23], v[12:15]
	global_load_dwordx4 v[20:23], v[46:47], off offset:384
	global_load_dwordx4 v[24:27], v[46:47], off offset:448
	s_waitcnt vmcnt(1)
	v_mfma_f32_16x16x32_bf16 v[4:7], v[20:23], v[32:35], v[4:7]
	global_load_dwordx4 v[32:35], v[50:51], off offset:384
	global_load_dwordx4 v[40:43], v[50:51], off offset:448
	v_mfma_f32_16x16x32_bf16 v[12:15], v[20:23], v[36:39], v[12:15]
	s_waitcnt vmcnt(1)
	v_mfma_f32_16x16x32_bf16 v[8:11], v[20:23], v[32:35], v[8:11]
	global_load_dwordx4 v[32:35], v[54:55], off offset:384
	global_load_dwordx4 v[36:39], v[54:55], off offset:448
	s_waitcnt vmcnt(2)
	v_mfma_f32_16x16x32_bf16 v[8:11], v[24:27], v[40:43], v[8:11]
	s_waitcnt vmcnt(1)
	v_mfma_f32_16x16x32_bf16 v[0:3], v[20:23], v[32:35], v[0:3]
	global_load_dwordx4 v[20:23], v[48:49], off offset:448
	global_load_dwordx4 v[32:35], v[48:49], off offset:512
	s_waitcnt vmcnt(2)
	v_mfma_f32_16x16x32_bf16 v[0:3], v[24:27], v[36:39], v[0:3]
	s_waitcnt vmcnt(1)
	v_mfma_f32_16x16x32_bf16 v[4:7], v[24:27], v[20:23], v[4:7]
	global_load_dwordx4 v[20:23], v[52:53], off offset:448
	global_load_dwordx4 v[40:43], v[52:53], off offset:512
	s_waitcnt vmcnt(1)
	v_mfma_f32_16x16x32_bf16 v[12:15], v[24:27], v[20:23], v[12:15]
	global_load_dwordx4 v[20:23], v[46:47], off offset:512
	global_load_dwordx4 v[24:27], v[46:47], off offset:576
	s_waitcnt vmcnt(1)
	v_mfma_f32_16x16x32_bf16 v[4:7], v[20:23], v[32:35], v[4:7]
	global_load_dwordx4 v[32:35], v[50:51], off offset:512
	global_load_dwordx4 v[36:39], v[50:51], off offset:576
	v_mfma_f32_16x16x32_bf16 v[12:15], v[20:23], v[40:43], v[12:15]
	s_waitcnt vmcnt(1)
	v_mfma_f32_16x16x32_bf16 v[8:11], v[20:23], v[32:35], v[8:11]
	global_load_dwordx4 v[32:35], v[54:55], off offset:512
	global_load_dwordx4 v[40:43], v[54:55], off offset:576
	s_waitcnt vmcnt(2)
	v_mfma_f32_16x16x32_bf16 v[8:11], v[24:27], v[36:39], v[8:11]
	v_mfma_f32_16x16x32_bf16 v[8:11], v[16:19], v[28:31], v[8:11]
	s_waitcnt vmcnt(1)
	v_mfma_f32_16x16x32_bf16 v[0:3], v[20:23], v[32:35], v[0:3]
	global_load_dwordx4 v[20:23], v[48:49], off offset:576
	global_load_dwordx4 v[32:35], v[48:49], off offset:640
	s_waitcnt vmcnt(2)
	v_mfma_f32_16x16x32_bf16 v[0:3], v[24:27], v[40:43], v[0:3]
	s_waitcnt vmcnt(1)
	v_mfma_f32_16x16x32_bf16 v[4:7], v[24:27], v[20:23], v[4:7]
	global_load_dwordx4 v[20:23], v[52:53], off offset:576
	global_load_dwordx4 v[36:39], v[52:53], off offset:640
	s_waitcnt vmcnt(2)
	v_mfma_f32_16x16x32_bf16 v[4:7], v[16:19], v[32:35], v[4:7]
	s_waitcnt vmcnt(1)
	v_mfma_f32_16x16x32_bf16 v[12:15], v[24:27], v[20:23], v[12:15]
	global_load_dwordx4 v[20:23], v[54:55], off offset:640
	v_add3_u32 v24, s0, v135, v186
	s_add_u32 s0, s66, s10
	s_waitcnt vmcnt(1)
	v_mfma_f32_16x16x32_bf16 v[12:15], v[16:19], v[36:39], v[12:15]
	s_addc_u32 s1, s67, 0
	ds_write2_b32 v24, v4, v8 offset1:16
	ds_write2_b32 v24, v5, v9 offset0:64 offset1:80
	ds_write2_b32 v24, v6, v10 offset0:128 offset1:144
	ds_write2_b32 v24, v7, v11 offset0:192 offset1:208
	s_add_u32 s3, s66, 0x38a0d000
	s_addc_u32 s33, s67, 0
	s_waitcnt vmcnt(0)
	v_mfma_f32_16x16x32_bf16 v[0:3], v[16:19], v[20:23], v[0:3]
	s_nop 7
	ds_write2_b32 v24, v12, v0 offset0:32 offset1:48
	ds_write2_b32 v24, v13, v1 offset0:96 offset1:112
	ds_write2_b32 v24, v14, v2 offset0:160 offset1:176
	ds_write2_b32 v24, v15, v3 offset0:224 offset1:240
	v_lshl_add_u64 v[0:1], s[0:1], 0, v[128:129]
	s_mov_b64 s[0:1], 0x30e00000
	v_lshl_add_u64 v[0:1], v[0:1], 0, s[0:1]
	v_lshl_add_u64 v[2:3], v[0:1], 0, v[130:131]
	s_waitcnt lgkmcnt(0)
	s_barrier
	v_lshl_add_u64 v[0:1], v[0:1], 0, v[132:133]
	v_mov_b32_e32 v16, v64
	v_mov_b32_e32 v17, v65
	ds_read2st64_b32 v[0:1], v173 offset1:8
	ds_read2st64_b32 v[2:3], v173 offset0:16 offset1:24
	ds_read2st64_b32 v[4:5], v173 offset0:32 offset1:40
	ds_read2st64_b32 v[6:7], v173 offset0:48 offset1:56
	ds_read2st64_b32 v[8:9], v173 offset0:64 offset1:72
	ds_read2st64_b32 v[10:11], v173 offset0:80 offset1:88
	ds_read2st64_b32 v[12:13], v173 offset0:96 offset1:104
	ds_read2st64_b32 v[14:15], v173 offset0:112 offset1:120
	s_waitcnt lgkmcnt(7)
	v_add_f32_e32 v0, 0, v0
	v_add_f32_e32 v1, 0, v1
	s_waitcnt lgkmcnt(6)
	v_add_f32_e32 v0, v0, v2
	v_add_f32_e32 v1, v1, v3
	s_waitcnt lgkmcnt(5)
	v_add_f32_e32 v0, v0, v4
	v_add_f32_e32 v1, v1, v5
	s_waitcnt lgkmcnt(4)
	v_add_f32_e32 v0, v0, v6
	v_add_f32_e32 v1, v1, v7
	s_waitcnt lgkmcnt(3)
	v_add_f32_e32 v0, v0, v8
	v_add_f32_e32 v1, v1, v9
	s_waitcnt lgkmcnt(2)
	v_add_f32_e32 v0, v0, v10
	v_add_f32_e32 v1, v1, v11
	s_waitcnt lgkmcnt(1)
	v_add_f32_e32 v0, v0, v12
	v_add_f32_e32 v1, v1, v13
	s_waitcnt lgkmcnt(0)
	v_add_f32_e32 v0, v0, v14
	v_add_f32_e32 v1, v1, v15
	s_waitcnt vmcnt(1)
	v_fmac_f32_e32 v0, 0x3f9837f0, v16
	s_waitcnt vmcnt(0)
	v_fmac_f32_e32 v1, 0x3f9837f0, v17
	global_store_dword v[136:137], v0, off sc1
	global_store_dword v[138:139], v1, off sc1
	s_barrier
